# FFN-in GEMM: first K-loop iteration peeled so the first MFMA into each accumulator takes C=0; the 128 accumulator-zeroing v_mov per tile are gone
# speedup vs baseline: 1.0118x; 1.0060x over previous
; #define PG8_STAGE(bufoff, gbase, voff) do { _Pragma("unroll") for (int _i = 0; _i < 2; ++_i) \
;         __builtin_amdgcn_global_load_lds((const unsigned*)((const char*)(gbase) + (voff)[_i]), (PG8_LAS unsigned*)(lds + (bufoff) + ldsw + _i * 8192), 16, 0, 0); } while (0)
; #define PG8_LDA(dst, b, h) do { _Pragma("unroll") for (int m = 0; m < 4; ++m) _Pragma("unroll") for (int k = 0; k < 2; ++k) dst[m][k] = *(const PG8_LAS bf16x8*)(lds + PG8_SA(b, h) + aoff + m * 2048 + k * 1024); } while (0)
; #define PG8_LDB(dst, b, h) do { _Pragma("unroll") for (int n = 0; n < 2; ++n) _Pragma("unroll") for (int k = 0; k < 2; ++k) dst[n][k] = *(const PG8_LAS bf16x8*)(lds + PG8_SB(b, h) + boff + n * 2048 + k * 1024); } while (0)
; #define PG8_MMA(ai, bj, At, Bt) do { __builtin_amdgcn_s_setprio(1); _Pragma("unroll") for (int m = 0; m < 4; ++m) _Pragma("unroll") for (int n = 0; n < 2; ++n) _Pragma("unroll") for (int k = 0; k < 2; ++k) \
;         acc[ai][bj][m][n] = __builtin_amdgcn_mfma_f32_16x16x32_bf16(Bt[n][k], At[m][k], acc[ai][bj][m][n], 0, 0, 0); __builtin_amdgcn_s_setprio(0); } while (0)
; #define PG8_WAIT_V(n) asm volatile("s_waitcnt vmcnt(" #n ")" ::: "memory")
; template <class Epi, class Sched, bool ALIGN_EPI = false, bool SP2 = false>
; __device__ __forceinline__ void gemm_phase(PG8_LAS unsigned char* lds, const Gemm g, const Sched& S, const Epi& E, const int tid_in) {
;     ...
;         const bool has_next = S.next(ui + 1, nxt);
;         const char* nA = has_next ? (const char*)g.A + (size_t)nxt.pm * tstep + (size_t)nxt.k0 * 2 : cA; const char* nB = has_next ? (const char*)g.Bt + (size_t)nxt.pn * tstep + (size_t)nxt.k0 * 2 : cB;
;         const int nt = cur.nt;
;         for (int t = 0; t < nt; t += 2) {
;             const bool last = (t == nt - 2);
;             const char* a1 = cA + (size_t)(t + 1) * kstep;
;             const char* a2 = last ? nA : cA + (size_t)(t + 2) * kstep; const char* b2 = last ? nB : cB + (size_t)(t + 2) * kstep;
;             const char* a3 = a2 + kstep; const char* b3 = b2 + kstep;
;             if (last && has_next) S.a_ready(nxt);
;             if constexpr (SP2) {
;             PG8_LDB(B0, 0, 0); PG8_LDB(B1, 0, 1); PG8_SCHED; PG8_LDA(At, 0, 0); PG8_STAGE(PG8_SA(1, 1), a1 + hstep, voffA);
;             PG8_WAIT_V(8); PG8_WAIT_L(0); PG8_BAR; PG8_MMA(0, 0, At, B0); PG8_MMA(0, 1, At, B1); PG8_BAR; PG8_SCHED;
.LBB0_306:
	s_add_i32 s38, s38, 1
	s_mul_i32 s2, s38, s73
	s_mul_hi_u32 s3, s38, s88
	s_add_i32 s3, s3, s2
	s_mul_i32 s2, s38, s88
	s_add_u32 s2, s2, s74
	s_addc_u32 s3, s3, s75
	v_mov_b64_e32 v[0:1], s[96:97]
	v_cmp_lt_i64_e64 s[6:7], s[2:3], v[0:1]
	s_mov_b64 s[4:5], s[16:17]
	s_and_b64 s[16:17], s[6:7], exec
	s_cselect_b32 s2, s2, 0
	s_ashr_i32 s3, s2, 31
	s_lshr_b32 s3, s3, 29
	s_add_i32 s3, s2, s3
	s_ashr_i32 s9, s3, 3
	s_and_b32 s3, s3, -8
	s_sub_i32 s2, s2, s3
	s_cmp_lt_i32 s2, 0
	s_cselect_b32 s3, s29, s28
	s_mul_i32 s2, s3, s2
	s_add_i32 s9, s2, s9
	s_mul_hi_i32 s2, s9, 0x2e8ba2e9
	s_lshr_b32 s3, s2, 31
	s_ashr_i32 s2, s2, 5
	s_add_i32 s11, s2, s3
	s_lshl_b32 s16, s11, 3
	s_sub_i32 s2, s24, s16
	s_min_i32 s17, s2, 8
	s_abs_i32 s22, s17
	v_cvt_f32_u32_e32 v0, s22
	s_mulk_i32 s11, 0xb0
	s_mov_b64 s[20:21], s[12:13]
	s_sub_i32 s9, s9, s11
	v_rcp_iflag_f32_e32 v0, v0
	s_sub_i32 s11, 0, s22
	s_mov_b32 s3, s10
	s_abs_i32 s10, s9
	v_mul_f32_e32 v0, 0x4f7ffffe, v0
	v_cvt_u32_f32_e32 v0, v0
	s_mov_b32 s2, s8
	s_xor_b32 s8, s9, s17
	s_ashr_i32 s8, s8, 31
	v_readfirstlane_b32 s12, v0
	s_mul_i32 s11, s11, s12
	s_mul_hi_u32 s11, s12, s11
	s_add_i32 s12, s12, s11
	s_mul_hi_u32 s11, s10, s12
	s_mul_i32 s12, s11, s22
	s_sub_i32 s10, s10, s12
	s_add_i32 s12, s11, 1
	s_sub_i32 s13, s10, s22
	s_cmp_ge_u32 s10, s22
	s_cselect_b32 s11, s12, s11
	s_cselect_b32 s10, s13, s10
	s_add_i32 s12, s11, 1
	s_cmp_ge_u32 s10, s22
	s_cselect_b32 s10, s12, s11
	s_xor_b32 s10, s10, s8
	s_sub_i32 s8, s10, s8
	s_mul_i32 s10, s8, s17
	s_sub_i32 s9, s9, s10
	s_add_i32 s10, s16, s9
	s_ashr_i32 s11, s10, 31
	s_lshl_b64 s[12:13], s[10:11], 19
	s_add_u32 s16, s50, s12
	s_addc_u32 s17, s51, s13
	s_and_b64 s[12:13], s[6:7], exec
	s_cselect_b32 s11, s17, s5
	s_cselect_b32 s39, s16, s4
	s_ashr_i32 s9, s8, 31
	s_lshl_b64 s[12:13], s[8:9], 19
	s_add_u32 s12, s25, s12
	s_addc_u32 s13, s26, s13
	s_and_b64 s[22:23], s[6:7], exec
	s_cselect_b32 s9, s13, s21
	s_cselect_b32 s40, s12, s20
	s_add_u32 s4, s4, 0x40080
	s_addc_u32 s5, s5, 0
	s_add_u32 s41, s20, 0x100
	s_addc_u32 s42, s21, 0
	s_mov_b32 s43, -2
	s_nop 0
	s_add_u32 s20, s4, 0xfffc0080
	s_addc_u32 s21, s5, -1
	s_add_i32 s44, 0, 0x10000
	s_cmp_eq_u32 s43, 12
	s_cselect_b32 s23, s11, s21
	s_cselect_b32 s22, s39, s20
	s_cselect_b32 s21, s9, s42
	s_cselect_b32 s20, s40, s41
	s_add_i32 s46, 0, 0x14000
	v_add_u32_e32 v154, s44, v143
	v_add_u32_e32 v170, s46, v143
	ds_read_b128 v[138:141], v154
	ds_read_b128 v[146:149], v154 offset:1024
	ds_read_b128 v[150:153], v154 offset:2048
	ds_read_b128 v[154:157], v154 offset:3072
	ds_read_b128 v[158:161], v170
	ds_read_b128 v[162:165], v170 offset:1024
	ds_read_b128 v[166:169], v170 offset:2048
	ds_read_b128 v[170:173], v170 offset:3072
	s_add_i32 m0, s30, 0xc000
	ds_read_b128 v[174:177], v145
	ds_read_b128 v[178:181], v145 offset:1024
	ds_read_b128 v[182:185], v145 offset:2048
	ds_read_b128 v[186:189], v145 offset:3072
	ds_read_b128 v[200:203], v145 offset:4096
	ds_read_b128 v[204:207], v145 offset:5120
	ds_read_b128 v[208:211], v145 offset:6144
	ds_read_b128 v[212:215], v145 offset:7168
	global_load_lds_dwordx4 v134, s[4:5]
	s_add_i32 m0, s30, 0xe000
	s_nop 0
	global_load_lds_dwordx4 v136, s[4:5]
	s_waitcnt vmcnt(8)
	s_waitcnt lgkmcnt(0)
	s_barrier
	s_setprio 1
	s_waitcnt lgkmcnt(0)
	v_mfma_f32_16x16x32_bf16 v[124:127], v[138:141], v[174:177], 0
	v_mfma_f32_16x16x32_bf16 v[116:119], v[150:153], v[174:177], 0
	v_mfma_f32_16x16x32_bf16 v[108:111], v[138:141], v[182:185], 0
	v_mfma_f32_16x16x32_bf16 v[100:103], v[150:153], v[182:185], 0
	v_mfma_f32_16x16x32_bf16 v[92:95], v[138:141], v[200:203], 0
	v_mfma_f32_16x16x32_bf16 v[84:87], v[150:153], v[200:203], 0
	v_mfma_f32_16x16x32_bf16 v[76:79], v[138:141], v[208:211], 0
	v_mfma_f32_16x16x32_bf16 v[68:71], v[150:153], v[208:211], 0
	v_mfma_f32_16x16x32_bf16 v[124:127], v[146:149], v[178:181], v[124:127]
	v_mfma_f32_16x16x32_bf16 v[116:119], v[154:157], v[178:181], v[116:119]
	v_mfma_f32_16x16x32_bf16 v[108:111], v[146:149], v[186:189], v[108:111]
	v_mfma_f32_16x16x32_bf16 v[100:103], v[154:157], v[186:189], v[100:103]
	v_mfma_f32_16x16x32_bf16 v[92:95], v[146:149], v[204:207], v[92:95]
	v_mfma_f32_16x16x32_bf16 v[84:87], v[154:157], v[204:207], v[84:87]
	v_mfma_f32_16x16x32_bf16 v[76:79], v[146:149], v[212:215], v[76:79]
	v_mfma_f32_16x16x32_bf16 v[68:71], v[154:157], v[212:215], v[68:71]
	s_setprio 0
	s_setprio 1
	v_mfma_f32_16x16x32_bf16 v[120:123], v[158:161], v[174:177], 0
	v_mfma_f32_16x16x32_bf16 v[112:115], v[166:169], v[174:177], 0
	v_mfma_f32_16x16x32_bf16 v[104:107], v[158:161], v[182:185], 0
	v_mfma_f32_16x16x32_bf16 v[96:99], v[166:169], v[182:185], 0
	v_mfma_f32_16x16x32_bf16 v[88:91], v[158:161], v[200:203], 0
	v_mfma_f32_16x16x32_bf16 v[80:83], v[166:169], v[200:203], 0
	v_mfma_f32_16x16x32_bf16 v[72:75], v[158:161], v[208:211], 0
	v_mfma_f32_16x16x32_bf16 v[64:67], v[166:169], v[208:211], 0
	v_mfma_f32_16x16x32_bf16 v[120:123], v[162:165], v[178:181], v[120:123]
	v_mfma_f32_16x16x32_bf16 v[112:115], v[170:173], v[178:181], v[112:115]
	v_mfma_f32_16x16x32_bf16 v[104:107], v[162:165], v[186:189], v[104:107]
	v_mfma_f32_16x16x32_bf16 v[96:99], v[170:173], v[186:189], v[96:99]
	v_mfma_f32_16x16x32_bf16 v[88:91], v[162:165], v[204:207], v[88:91]
	v_mfma_f32_16x16x32_bf16 v[80:83], v[170:173], v[204:207], v[80:83]
	v_mfma_f32_16x16x32_bf16 v[72:75], v[162:165], v[212:215], v[72:75]
	v_mfma_f32_16x16x32_bf16 v[64:67], v[170:173], v[212:215], v[64:67]
	s_setprio 0
	s_barrier
; #define PG8_STAGE(bufoff, gbase, voff) do { _Pragma("unroll") for (int _i = 0; _i < 2; ++_i) \
;         __builtin_amdgcn_global_load_lds((const unsigned*)((const char*)(gbase) + (voff)[_i]), (PG8_LAS unsigned*)(lds + (bufoff) + ldsw + _i * 8192), 16, 0, 0); } while (0)
; #define PG8_LDA(dst, b, h) do { _Pragma("unroll") for (int m = 0; m < 4; ++m) _Pragma("unroll") for (int k = 0; k < 2; ++k) dst[m][k] = *(const PG8_LAS bf16x8*)(lds + PG8_SA(b, h) + aoff + m * 2048 + k * 1024); } while (0)
; #define PG8_LDB(dst, b, h) do { _Pragma("unroll") for (int n = 0; n < 2; ++n) _Pragma("unroll") for (int k = 0; k < 2; ++k) dst[n][k] = *(const PG8_LAS bf16x8*)(lds + PG8_SB(b, h) + boff + n * 2048 + k * 1024); } while (0)
; #define PG8_MMA(ai, bj, At, Bt) do { __builtin_amdgcn_s_setprio(1); _Pragma("unroll") for (int m = 0; m < 4; ++m) _Pragma("unroll") for (int n = 0; n < 2; ++n) _Pragma("unroll") for (int k = 0; k < 2; ++k) \
;         acc[ai][bj][m][n] = __builtin_amdgcn_mfma_f32_16x16x32_bf16(Bt[n][k], At[m][k], acc[ai][bj][m][n], 0, 0, 0); __builtin_amdgcn_s_setprio(0); } while (0)
; #define PG8_WAIT_V(n) asm volatile("s_waitcnt vmcnt(" #n ")" ::: "memory")
; #define PG8_WAIT_L(n) asm volatile("s_waitcnt lgkmcnt(" #n ")" ::: "memory")
; #define PG8_BAR __builtin_amdgcn_s_barrier()
; #define PG8_SCHED __builtin_amdgcn_sched_barrier(0)
; template <class Epi, class Sched, bool ALIGN_EPI = false, bool SP2 = false>
; __device__ __forceinline__ void gemm_phase(PG8_LAS unsigned char* lds, const Gemm g, const Sched& S, const Epi& E, const int tid_in) {
;     ...
;             PG8_WAIT_V(8); PG8_WAIT_L(0); PG8_BAR; PG8_MMA(0, 0, At, B0); PG8_MMA(0, 1, At, B1); PG8_BAR; PG8_SCHED;
;             PG8_LDA(At, 0, 1); PG8_STAGE(PG8_SB(0, 0), b2, voffB); PG8_STAGE(PG8_SB(0, 1), b2 + hstep, voffB); PG8_STAGE(PG8_SA(0, 0), a2, voffA);
;             PG8_WAIT_V(8); PG8_WAIT_L(0); PG8_BAR; PG8_MMA(1, 0, At, B0); PG8_MMA(1, 1, At, B1); PG8_BAR; PG8_SCHED;
;             PG8_LDB(B0, 1, 0); PG8_LDB(B1, 1, 1); PG8_SCHED; PG8_LDA(At, 1, 0); PG8_STAGE(PG8_SA(0, 1), a2 + hstep, voffA);
	s_add_i32 s44, s44, s27
	s_mov_b32 m0, s44
	ds_read_b128 v[174:177], v145 offset:16384
	ds_read_b128 v[178:181], v145 offset:17408
	ds_read_b128 v[182:185], v145 offset:18432
	ds_read_b128 v[186:189], v145 offset:19456
	ds_read_b128 v[200:203], v145 offset:20480
	ds_read_b128 v[204:207], v145 offset:21504
	ds_read_b128 v[208:211], v145 offset:22528
	ds_read_b128 v[212:215], v145 offset:23552
	global_load_lds_dwordx4 v192, s[20:21]
	s_add_i32 m0, s44, 0x2000
	s_add_u32 s44, s20, 0x40000
	s_addc_u32 s45, s21, 0
	s_add_i32 s46, s46, s27
	global_load_lds_dwordx4 v128, s[20:21]
	s_mov_b32 m0, s46
	s_nop 0
	global_load_lds_dwordx4 v192, s[44:45]
	s_add_i32 m0, s46, 0x2000
	s_nop 0
	global_load_lds_dwordx4 v128, s[44:45]
	s_mov_b32 m0, s30
	s_nop 0
	global_load_lds_dwordx4 v132, s[22:23]
	s_mov_b32 m0, s31
	s_nop 0
	global_load_lds_dwordx4 v130, s[22:23]
	s_waitcnt vmcnt(8)
	s_waitcnt lgkmcnt(0)
	s_barrier
	s_setprio 1
	s_waitcnt lgkmcnt(0)
	v_mfma_f32_16x16x32_bf16 v[60:63], v[138:141], v[174:177], 0
	v_mfma_f32_16x16x32_bf16 v[52:55], v[150:153], v[174:177], 0
	v_mfma_f32_16x16x32_bf16 v[44:47], v[138:141], v[182:185], 0
	v_mfma_f32_16x16x32_bf16 v[36:39], v[150:153], v[182:185], 0
	v_mfma_f32_16x16x32_bf16 v[28:31], v[138:141], v[200:203], 0
	v_mfma_f32_16x16x32_bf16 v[20:23], v[150:153], v[200:203], 0
	v_mfma_f32_16x16x32_bf16 v[12:15], v[138:141], v[208:211], 0
	v_mfma_f32_16x16x32_bf16 v[4:7], v[150:153], v[208:211], 0
	v_mfma_f32_16x16x32_bf16 v[60:63], v[146:149], v[178:181], v[60:63]
	v_mfma_f32_16x16x32_bf16 v[52:55], v[154:157], v[178:181], v[52:55]
	v_mfma_f32_16x16x32_bf16 v[44:47], v[146:149], v[186:189], v[44:47]
	v_mfma_f32_16x16x32_bf16 v[36:39], v[154:157], v[186:189], v[36:39]
	v_mfma_f32_16x16x32_bf16 v[28:31], v[146:149], v[204:207], v[28:31]
	v_mfma_f32_16x16x32_bf16 v[20:23], v[154:157], v[204:207], v[20:23]
	v_mfma_f32_16x16x32_bf16 v[12:15], v[146:149], v[212:215], v[12:15]
	v_mfma_f32_16x16x32_bf16 v[4:7], v[154:157], v[212:215], v[4:7]
	s_setprio 0
	s_setprio 1
	v_mfma_f32_16x16x32_bf16 v[56:59], v[158:161], v[174:177], 0
	v_mfma_f32_16x16x32_bf16 v[48:51], v[166:169], v[174:177], 0
	v_mfma_f32_16x16x32_bf16 v[40:43], v[158:161], v[182:185], 0
	v_mfma_f32_16x16x32_bf16 v[32:35], v[166:169], v[182:185], 0
	v_mfma_f32_16x16x32_bf16 v[24:27], v[158:161], v[200:203], 0
	v_mfma_f32_16x16x32_bf16 v[16:19], v[166:169], v[200:203], 0
	v_mfma_f32_16x16x32_bf16 v[8:11], v[158:161], v[208:211], 0
	v_mfma_f32_16x16x32_bf16 v[0:3], v[166:169], v[208:211], 0
	v_mfma_f32_16x16x32_bf16 v[56:59], v[162:165], v[178:181], v[56:59]
	v_mfma_f32_16x16x32_bf16 v[48:51], v[170:173], v[178:181], v[48:51]
	v_mfma_f32_16x16x32_bf16 v[40:43], v[162:165], v[186:189], v[40:43]
	v_mfma_f32_16x16x32_bf16 v[32:35], v[170:173], v[186:189], v[32:35]
	v_mfma_f32_16x16x32_bf16 v[24:27], v[162:165], v[204:207], v[24:27]
	v_mfma_f32_16x16x32_bf16 v[16:19], v[170:173], v[204:207], v[16:19]
	v_mfma_f32_16x16x32_bf16 v[8:11], v[162:165], v[212:215], v[8:11]
	v_mfma_f32_16x16x32_bf16 v[0:3], v[170:173], v[212:215], v[0:3]
	s_setprio 0
	s_barrier
	s_add_i32 s44, 0, 0x18000
	s_add_i32 s45, 0, 0x1c000
	v_add_u32_e32 v154, s44, v143
	v_add_u32_e32 v170, s45, v143
	ds_read_b128 v[138:141], v154
	ds_read_b128 v[146:149], v154 offset:1024
	ds_read_b128 v[150:153], v154 offset:2048
	ds_read_b128 v[154:157], v154 offset:3072
	ds_read_b128 v[158:161], v170
	ds_read_b128 v[162:165], v170 offset:1024
	ds_read_b128 v[166:169], v170 offset:2048
	ds_read_b128 v[170:173], v170 offset:3072
	s_add_u32 s22, s22, 0x40000
	s_addc_u32 s23, s23, 0
	s_mov_b32 m0, s34
	ds_read_b128 v[174:177], v145 offset:32768
	ds_read_b128 v[178:181], v145 offset:33792
	ds_read_b128 v[182:185], v145 offset:34816
	ds_read_b128 v[186:189], v145 offset:35840
	ds_read_b128 v[200:203], v145 offset:36864
	ds_read_b128 v[204:207], v145 offset:37888
	ds_read_b128 v[208:211], v145 offset:38912
	ds_read_b128 v[212:215], v145 offset:39936
	global_load_lds_dwordx4 v132, s[22:23]
	s_mov_b32 m0, s35
	s_nop 0
	global_load_lds_dwordx4 v130, s[22:23]
	s_waitcnt vmcnt(8)
	s_waitcnt lgkmcnt(0)
	s_barrier
; #define PG8_STAGE(bufoff, gbase, voff) do { _Pragma("unroll") for (int _i = 0; _i < 2; ++_i) \
;         __builtin_amdgcn_global_load_lds((const unsigned*)((const char*)(gbase) + (voff)[_i]), (PG8_LAS unsigned*)(lds + (bufoff) + ldsw + _i * 8192), 16, 0, 0); } while (0)
; #define PG8_LDA(dst, b, h) do { _Pragma("unroll") for (int m = 0; m < 4; ++m) _Pragma("unroll") for (int k = 0; k < 2; ++k) dst[m][k] = *(const PG8_LAS bf16x8*)(lds + PG8_SA(b, h) + aoff + m * 2048 + k * 1024); } while (0)
; #define PG8_MMA(ai, bj, At, Bt) do { __builtin_amdgcn_s_setprio(1); _Pragma("unroll") for (int m = 0; m < 4; ++m) _Pragma("unroll") for (int n = 0; n < 2; ++n) _Pragma("unroll") for (int k = 0; k < 2; ++k) \
;         acc[ai][bj][m][n] = __builtin_amdgcn_mfma_f32_16x16x32_bf16(Bt[n][k], At[m][k], acc[ai][bj][m][n], 0, 0, 0); __builtin_amdgcn_s_setprio(0); } while (0)
; #define PG8_WAIT_V(n) asm volatile("s_waitcnt vmcnt(" #n ")" ::: "memory")
; #define PG8_WAIT_L(n) asm volatile("s_waitcnt lgkmcnt(" #n ")" ::: "memory")
; #define PG8_BAR __builtin_amdgcn_s_barrier()
; #define PG8_SCHED __builtin_amdgcn_sched_barrier(0)
; template <class Epi, class Sched, bool ALIGN_EPI = false, bool SP2 = false>
; __device__ __forceinline__ void gemm_phase(PG8_LAS unsigned char* lds, const Gemm g, const Sched& S, const Epi& E, const int tid_in) {
;     ...
;         for (int t = 0; t < nt; t += 2) {
;     ...
;             PG8_WAIT_V(8); PG8_WAIT_L(0); PG8_BAR; PG8_MMA(0, 0, At, B0); PG8_MMA(0, 1, At, B1); PG8_BAR; PG8_SCHED;
;             PG8_LDA(At, 1, 1); PG8_STAGE(PG8_SB(1, 0), b3, voffB); PG8_STAGE(PG8_SB(1, 1), b3 + hstep, voffB); PG8_STAGE(PG8_SA(1, 0), a3, voffA);
;             PG8_WAIT_V(8); PG8_WAIT_L(0); PG8_BAR; PG8_MMA(1, 0, At, B0); PG8_MMA(1, 1, At, B1); PG8_BAR; PG8_SCHED;
	s_setprio 1
	s_waitcnt lgkmcnt(0)
	v_mfma_f32_16x16x32_bf16 v[124:127], v[138:141], v[174:177], v[124:127]
	v_mfma_f32_16x16x32_bf16 v[116:119], v[150:153], v[174:177], v[116:119]
	v_mfma_f32_16x16x32_bf16 v[108:111], v[138:141], v[182:185], v[108:111]
	v_mfma_f32_16x16x32_bf16 v[100:103], v[150:153], v[182:185], v[100:103]
	v_mfma_f32_16x16x32_bf16 v[92:95], v[138:141], v[200:203], v[92:95]
	v_mfma_f32_16x16x32_bf16 v[84:87], v[150:153], v[200:203], v[84:87]
	v_mfma_f32_16x16x32_bf16 v[76:79], v[138:141], v[208:211], v[76:79]
	v_mfma_f32_16x16x32_bf16 v[68:71], v[150:153], v[208:211], v[68:71]
	v_mfma_f32_16x16x32_bf16 v[124:127], v[146:149], v[178:181], v[124:127]
	v_mfma_f32_16x16x32_bf16 v[116:119], v[154:157], v[178:181], v[116:119]
	v_mfma_f32_16x16x32_bf16 v[108:111], v[146:149], v[186:189], v[108:111]
	v_mfma_f32_16x16x32_bf16 v[100:103], v[154:157], v[186:189], v[100:103]
	v_mfma_f32_16x16x32_bf16 v[92:95], v[146:149], v[204:207], v[92:95]
	v_mfma_f32_16x16x32_bf16 v[84:87], v[154:157], v[204:207], v[84:87]
	v_mfma_f32_16x16x32_bf16 v[76:79], v[146:149], v[212:215], v[76:79]
	v_mfma_f32_16x16x32_bf16 v[68:71], v[154:157], v[212:215], v[68:71]
	s_setprio 0
	s_setprio 1
	v_mfma_f32_16x16x32_bf16 v[120:123], v[158:161], v[174:177], v[120:123]
	v_mfma_f32_16x16x32_bf16 v[112:115], v[166:169], v[174:177], v[112:115]
	v_mfma_f32_16x16x32_bf16 v[104:107], v[158:161], v[182:185], v[104:107]
	v_mfma_f32_16x16x32_bf16 v[96:99], v[166:169], v[182:185], v[96:99]
	v_mfma_f32_16x16x32_bf16 v[88:91], v[158:161], v[200:203], v[88:91]
	v_mfma_f32_16x16x32_bf16 v[80:83], v[166:169], v[200:203], v[80:83]
	v_mfma_f32_16x16x32_bf16 v[72:75], v[158:161], v[208:211], v[72:75]
	v_mfma_f32_16x16x32_bf16 v[64:67], v[166:169], v[208:211], v[64:67]
	v_mfma_f32_16x16x32_bf16 v[120:123], v[162:165], v[178:181], v[120:123]
	v_mfma_f32_16x16x32_bf16 v[112:115], v[170:173], v[178:181], v[112:115]
	v_mfma_f32_16x16x32_bf16 v[104:107], v[162:165], v[186:189], v[104:107]
	v_mfma_f32_16x16x32_bf16 v[96:99], v[170:173], v[186:189], v[96:99]
	v_mfma_f32_16x16x32_bf16 v[88:91], v[162:165], v[204:207], v[88:91]
	v_mfma_f32_16x16x32_bf16 v[80:83], v[170:173], v[204:207], v[80:83]
	v_mfma_f32_16x16x32_bf16 v[72:75], v[162:165], v[212:215], v[72:75]
	v_mfma_f32_16x16x32_bf16 v[64:67], v[170:173], v[212:215], v[64:67]
	s_setprio 0
	s_barrier
	s_sub_u32 s22, s22, 0x3ff80
	s_subb_u32 s23, s23, 0
	s_add_u32 s20, s20, 0x80
	s_addc_u32 s21, s21, 0
	s_add_i32 s46, s44, s27
	s_mov_b32 m0, s46
	ds_read_b128 v[174:177], v145 offset:49152
	ds_read_b128 v[178:181], v145 offset:50176
	ds_read_b128 v[182:185], v145 offset:51200
	ds_read_b128 v[186:189], v145 offset:52224
	ds_read_b128 v[200:203], v145 offset:53248
	ds_read_b128 v[204:207], v145 offset:54272
	ds_read_b128 v[208:211], v145 offset:55296
	ds_read_b128 v[212:215], v145 offset:56320
	global_load_lds_dwordx4 v192, s[20:21]
	s_add_i32 m0, s46, 0x2000
	s_add_i32 s46, s45, s27
	global_load_lds_dwordx4 v128, s[20:21]
	s_add_u32 s20, s20, 0x40000
	s_addc_u32 s21, s21, 0
	s_mov_b32 m0, s46
	s_nop 0
	global_load_lds_dwordx4 v192, s[20:21]
	s_add_i32 m0, s46, 0x2000
	s_nop 0
	global_load_lds_dwordx4 v128, s[20:21]
	s_mov_b32 m0, s36
	s_nop 0
	global_load_lds_dwordx4 v132, s[22:23]
	s_mov_b32 m0, s37
	s_nop 0
	global_load_lds_dwordx4 v130, s[22:23]
	s_waitcnt vmcnt(8)
	s_waitcnt lgkmcnt(0)
	s_barrier
	s_setprio 1
	s_waitcnt lgkmcnt(0)
	v_mfma_f32_16x16x32_bf16 v[60:63], v[138:141], v[174:177], v[60:63]
	v_mfma_f32_16x16x32_bf16 v[52:55], v[150:153], v[174:177], v[52:55]
	v_mfma_f32_16x16x32_bf16 v[44:47], v[138:141], v[182:185], v[44:47]
	v_mfma_f32_16x16x32_bf16 v[36:39], v[150:153], v[182:185], v[36:39]
	v_mfma_f32_16x16x32_bf16 v[28:31], v[138:141], v[200:203], v[28:31]
	v_mfma_f32_16x16x32_bf16 v[20:23], v[150:153], v[200:203], v[20:23]
	v_mfma_f32_16x16x32_bf16 v[12:15], v[138:141], v[208:211], v[12:15]
	v_mfma_f32_16x16x32_bf16 v[4:7], v[150:153], v[208:211], v[4:7]
	v_mfma_f32_16x16x32_bf16 v[60:63], v[146:149], v[178:181], v[60:63]
	v_mfma_f32_16x16x32_bf16 v[52:55], v[154:157], v[178:181], v[52:55]
	v_mfma_f32_16x16x32_bf16 v[44:47], v[146:149], v[186:189], v[44:47]
	v_mfma_f32_16x16x32_bf16 v[36:39], v[154:157], v[186:189], v[36:39]
	v_mfma_f32_16x16x32_bf16 v[28:31], v[146:149], v[204:207], v[28:31]
	v_mfma_f32_16x16x32_bf16 v[20:23], v[154:157], v[204:207], v[20:23]
	v_mfma_f32_16x16x32_bf16 v[12:15], v[146:149], v[212:215], v[12:15]
	v_mfma_f32_16x16x32_bf16 v[4:7], v[154:157], v[212:215], v[4:7]
	s_setprio 0
	s_setprio 1
	v_mfma_f32_16x16x32_bf16 v[56:59], v[158:161], v[174:177], v[56:59]
	v_mfma_f32_16x16x32_bf16 v[48:51], v[166:169], v[174:177], v[48:51]
	v_mfma_f32_16x16x32_bf16 v[40:43], v[158:161], v[182:185], v[40:43]
	v_mfma_f32_16x16x32_bf16 v[32:35], v[166:169], v[182:185], v[32:35]
	v_mfma_f32_16x16x32_bf16 v[24:27], v[158:161], v[200:203], v[24:27]
	v_mfma_f32_16x16x32_bf16 v[16:19], v[166:169], v[200:203], v[16:19]
	v_mfma_f32_16x16x32_bf16 v[8:11], v[158:161], v[208:211], v[8:11]
	v_mfma_f32_16x16x32_bf16 v[0:3], v[166:169], v[208:211], v[0:3]
	v_mfma_f32_16x16x32_bf16 v[56:59], v[162:165], v[178:181], v[56:59]
	v_mfma_f32_16x16x32_bf16 v[48:51], v[170:173], v[178:181], v[48:51]
	v_mfma_f32_16x16x32_bf16 v[40:43], v[162:165], v[186:189], v[40:43]
	v_mfma_f32_16x16x32_bf16 v[32:35], v[170:173], v[186:189], v[32:35]
	v_mfma_f32_16x16x32_bf16 v[24:27], v[162:165], v[204:207], v[24:27]
	v_mfma_f32_16x16x32_bf16 v[16:19], v[170:173], v[204:207], v[16:19]
	v_mfma_f32_16x16x32_bf16 v[8:11], v[162:165], v[212:215], v[8:11]
	v_mfma_f32_16x16x32_bf16 v[0:3], v[170:173], v[212:215], v[0:3]
	s_setprio 0
	s_barrier
	s_add_i32 s43, s43, 2
	s_add_u32 s4, s4, 0x100
	s_addc_u32 s5, s5, 0
	s_add_u32 s41, s41, 0x100
	s_addc_u32 s42, s42, 0
	s_cmp_gt_u32 s43, 13
	s_cbranch_scc0 .LBB0_307
	s_branch gk307_exit

; #define PG8_BAR __builtin_amdgcn_s_barrier()
; template <class Epi, class Sched, bool ALIGN_EPI = false, bool SP2 = false>
; __device__ __forceinline__ void gemm_phase(PG8_LAS unsigned char* lds, const Gemm g, const Sched& S, const Epi& E, const int tid_in) {
;     ...
;         if constexpr (ALIGN_EPI) { if (wr == 0) PG8_BAR; }
gk307_exit:
	s_and_b64 vcc, exec, s[18:19]
	s_cbranch_vccz .LBB0_310
	s_barrier
